# previous combo + P7 tile loops: the six tile-invariant LDS-DMA lane offsets kept in free VGPRs v243-v248 instead of 25 VALU ops per tile
# speedup vs baseline: 1.0317x; 1.0086x over previous
.LBB0_728:
	s_lshr_b32 s0, s7, 3
	v_writelane_b32 v255, s0, 13
	v_writelane_b32 v255, s7, 14
	s_bfe_u32 s1, s7, 0x40003
	v_writelane_b32 v255, s1, 15
	s_lshl_b32 s0, s1, 1
	s_lshl_b32 s1, s1, 7
	v_readlane_b32 s4, v255, 6
	s_lshl_b32 s7, s6, 11
	s_mulk_i32 s6, 0xc0
	s_or_b32 s1, s4, s1
	s_ashr_i32 s5, s6, 31
	s_ashr_i32 s8, s3, 31
	s_add_u32 s4, s6, s3
	s_addc_u32 s5, s5, s8
	v_add_u32_e32 v1, s85, v216
	v_ashrrev_i32_e32 v2, 4, v1
	s_lshl_b64 s[4:5], s[4:5], 17
	v_readlane_b32 s8, v254, 45
	v_xor_b32_e32 v5, v2, v216
	v_readlane_b32 s9, v254, 46
	s_add_u32 s94, s8, s4
	v_lshlrev_b32_e32 v2, 9, v2
	v_lshlrev_b32_e32 v5, 4, v5
	v_ashrrev_i32_e32 v6, 5, v1
	s_addc_u32 s95, s9, s5
	v_readlane_b32 s8, v254, 47
	v_and_or_b32 v2, v5, s2, v2
	v_lshlrev_b32_e32 v5, 4, v1
	v_lshrrev_b32_e32 v7, 2, v1
	v_and_b32_e32 v8, 0x7ffff0, v6
	v_lshrrev_b32_e32 v9, 1, v1
	v_lshrrev_b32_e32 v6, 1, v6
	v_lshlrev_b32_e32 v1, 1, v1
	v_readlane_b32 s9, v254, 48
	s_add_u32 s90, s8, s4
	v_and_b32_e32 v9, 8, v9
	v_and_b32_e32 v6, 4, v6
	v_and_or_b32 v7, v7, 3, v8
	v_and_b32_e32 v1, 0x1c0, v1
	s_addc_u32 s91, s9, s5
	s_add_i32 s74, s0, 2
	v_or3_b32 v6, v7, v6, v9
	v_and_or_b32 v1, v5, 48, v1
	s_add_u32 s88, s94, 0x100
	v_lshl_or_b32 v1, v6, 9, v1
	s_addc_u32 s89, s95, 0
	s_lshl_b32 s3, s3, 8
	v_ashrrev_i32_e32 v218, 5, v216
	v_add_u32_e32 v5, 0x2000, v1
	v_add_u32_e32 v6, 0x4000, v1
	v_add_u32_e32 v7, 0x6000, v1
	v_add_u32_e32 v8, 0x4000, v2
	v_readlane_b32 s5, v254, 62
	s_mov_b32 s4, m0
	s_mov_b32 m0, s5
	s_nop 0
	global_load_lds_dwordx4 v2, s[94:95]
	s_add_u32 m0, m0, 0x2000
	s_nop 0
	global_load_lds_dwordx4 v8, s[94:95]
	s_add_u32 m0, m0, 0x2000
	s_nop 0
	global_load_lds_dwordx4 v2, s[88:89]
	s_add_u32 m0, m0, 0x2000
	s_nop 0
	global_load_lds_dwordx4 v8, s[88:89]
	s_add_u32 m0, m0, 0x2000
	s_nop 0
	global_load_lds_dwordx4 v1, s[90:91]
	s_add_u32 m0, m0, 0x2000
	s_nop 0
	global_load_lds_dwordx4 v5, s[90:91]
	s_add_u32 m0, m0, 0x2000
	s_nop 0
	global_load_lds_dwordx4 v6, s[90:91]
	s_add_u32 m0, m0, 0x2000
	s_nop 0
	global_load_lds_dwordx4 v7, s[90:91]
	s_mov_b32 m0, s4
	v_mov_b32_e32 v243, v2
	v_mov_b32_e32 v244, v8
	v_mov_b32_e32 v245, v1
	v_mov_b32_e32 v246, v5
	v_mov_b32_e32 v247, v6
	v_mov_b32_e32 v248, v7
	s_add_i32 s3, s3, s20
	s_or_b32 s4, s7, s1
	v_lshl_add_u32 v5, v218, 3, s3
	v_and_b32_e32 v217, 31, v216
	v_writelane_b32 v255, s3, 16
	s_ashr_i32 s3, s4, 8
	v_ashrrev_i32_e32 v2, 8, v5
	v_or_b32_e32 v1, s1, v217
	v_writelane_b32 v255, s4, 17
	v_mad_u64_u32 v[6:7], s[4:5], s3, 24, v[2:3]
	v_ashrrev_i32_e32 v7, 31, v6
	v_lshlrev_b32_e32 v1, 8, v1
	v_and_b32_e32 v2, 0xf8, v5
	s_mov_b32 s3, 0xff00
	v_readlane_b32 s4, v254, 41
	v_and_or_b32 v1, v1, s3, v2
	v_lshlrev_b64 v[6:7], 17, v[6:7]
	v_readlane_b32 s5, v254, 42
	v_lshlrev_b32_e32 v2, 1, v1
	v_exp_f32_e32 v1, v4
	v_lshl_add_u64 v[6:7], s[4:5], 0, v[6:7]
	v_lshl_add_u64 v[6:7], v[6:7], 0, v[2:3]
	global_load_dwordx4 v[178:181], v[6:7], off
	global_load_dwordx4 v[182:185], v[6:7], off offset:32
	global_load_dwordx4 v[186:189], v[6:7], off offset:64
	global_load_dwordx4 v[190:193], v[6:7], off offset:96
	global_load_dwordx4 v[194:197], v[6:7], off offset:128
	global_load_dwordx4 v[198:201], v[6:7], off offset:160
	global_load_dwordx4 v[202:205], v[6:7], off offset:192
	global_load_dwordx4 v[206:209], v[6:7], off offset:224
	v_lshlrev_b32_e32 v219, 3, v216
	v_lshlrev_b32_e32 v220, 4, v216
	v_lshlrev_b32_e32 v2, 1, v216
	v_and_b32_e32 v5, 0x118, v219
	v_and_b32_e32 v4, 0xc0, v220
	v_lshlrev_b32_e32 v221, 4, v218
	v_and_or_b32 v2, v2, 32, v5
	v_readlane_b32 s6, v255, 8
	v_readlane_b32 s3, v255, 1
	v_add_u32_e32 v6, 32, v221
	v_add_u32_e32 v7, 64, v221
	v_add_u32_e32 v8, 0x60, v221
	v_add_u32_e32 v9, 0x80, v221
	v_add_u32_e32 v10, 0xa0, v221
	v_add_u32_e32 v11, 0xc0, v221
	v_add_u32_e32 v12, 0xe0, v221
	v_mul_f32_e32 v232, 0x3fb8aa3b, v1
	v_lshlrev_b32_e32 v1, 2, v218
	v_add3_u32 v233, v4, s6, v2
	v_add_u32_e32 v2, s1, v217
	v_mov_b32_e32 v16, v3
	v_mov_b32_e32 v17, v3
	v_lshl_add_u32 v222, v217, 8, s3
	v_readlane_b32 s3, v254, 61
	v_bitop3_b32 v225, v6, v220, s2 bitop3:0x78
	v_bitop3_b32 v226, v7, v220, s2 bitop3:0x78
	v_bitop3_b32 v227, v8, v220, s2 bitop3:0x78
	v_bitop3_b32 v228, v9, v220, s2 bitop3:0x78
	v_bitop3_b32 v229, v10, v220, s2 bitop3:0x78
	v_bitop3_b32 v230, v11, v220, s2 bitop3:0x78
	v_bitop3_b32 v231, v12, v220, s2 bitop3:0x78
	v_sub_u32_e32 v234, v2, v1
	v_mov_b32_e32 v2, v3
	v_mov_b32_e32 v4, v3
	v_mov_b32_e32 v5, v3
	v_mov_b32_e32 v6, v3
	v_mov_b32_e32 v7, v3
	v_mov_b32_e32 v8, v3
	v_mov_b32_e32 v9, v3
	v_mov_b32_e32 v10, v3
	v_mov_b32_e32 v11, v3
	v_mov_b32_e32 v12, v3
	v_mov_b32_e32 v13, v3
	v_mov_b32_e32 v14, v3
	v_mov_b32_e32 v15, v3
	v_mov_b64_e32 v[128:129], v[16:17]
	v_mov_b64_e32 v[96:97], v[16:17]
	v_mov_b64_e32 v[64:65], v[16:17]
	v_mov_b64_e32 v[32:33], v[16:17]
	v_mov_b64_e32 v[144:145], v[16:17]
	v_mov_b64_e32 v[112:113], v[16:17]
	v_mov_b64_e32 v[80:81], v[16:17]
	v_mov_b64_e32 v[48:49], v[16:17]
	s_movk_i32 s75, 0x4000
	v_cmp_gt_u32_e64 s[4:5], 32, v216
	v_lshl_add_u32 v223, v217, 2, s3
	v_bitop3_b32 v224, v220, v221, s2 bitop3:0x6c
	s_or_b32 s3, s1, 31
	s_mov_b32 s71, 0
	v_mov_b32_e32 v235, 0xf149f2ca
	v_mov_b32_e32 v236, 0
	s_mov_b32 s72, 63
	s_mov_b32 s76, -2
	v_mov_b64_e32 v[126:127], v[14:15]
	v_mov_b64_e32 v[124:125], v[12:13]
	v_mov_b64_e32 v[122:123], v[10:11]
	v_mov_b64_e32 v[120:121], v[8:9]
	v_mov_b64_e32 v[118:119], v[6:7]
	v_mov_b64_e32 v[116:117], v[4:5]
	v_mov_b64_e32 v[114:115], v[2:3]
	v_mov_b64_e32 v[94:95], v[14:15]
	v_mov_b64_e32 v[92:93], v[12:13]
	v_mov_b64_e32 v[90:91], v[10:11]
	v_mov_b64_e32 v[88:89], v[8:9]
	v_mov_b64_e32 v[86:87], v[6:7]
	v_mov_b64_e32 v[84:85], v[4:5]
	v_mov_b64_e32 v[82:83], v[2:3]
	v_mov_b64_e32 v[62:63], v[14:15]
	v_mov_b64_e32 v[60:61], v[12:13]
	v_mov_b64_e32 v[58:59], v[10:11]
	v_mov_b64_e32 v[56:57], v[8:9]
	v_mov_b64_e32 v[54:55], v[6:7]
	v_mov_b64_e32 v[52:53], v[4:5]
	v_mov_b64_e32 v[50:51], v[2:3]
	v_mov_b64_e32 v[30:31], v[14:15]
	v_mov_b64_e32 v[28:29], v[12:13]
	v_mov_b64_e32 v[26:27], v[10:11]
	v_mov_b64_e32 v[24:25], v[8:9]
	v_mov_b64_e32 v[22:23], v[6:7]
	v_mov_b64_e32 v[20:21], v[4:5]
	v_mov_b64_e32 v[18:19], v[2:3]
	v_mov_b64_e32 v[142:143], v[14:15]
	v_mov_b64_e32 v[140:141], v[12:13]
	v_mov_b64_e32 v[138:139], v[10:11]
	v_mov_b64_e32 v[136:137], v[8:9]
	v_mov_b64_e32 v[134:135], v[6:7]
	v_mov_b64_e32 v[132:133], v[4:5]
	v_mov_b64_e32 v[130:131], v[2:3]
	v_mov_b64_e32 v[110:111], v[14:15]
	v_mov_b64_e32 v[108:109], v[12:13]
	v_mov_b64_e32 v[106:107], v[10:11]
	v_mov_b64_e32 v[104:105], v[8:9]
	v_mov_b64_e32 v[102:103], v[6:7]
	v_mov_b64_e32 v[100:101], v[4:5]
	v_mov_b64_e32 v[98:99], v[2:3]
	v_mov_b64_e32 v[78:79], v[14:15]
	v_mov_b64_e32 v[76:77], v[12:13]
	v_mov_b64_e32 v[74:75], v[10:11]
	v_mov_b64_e32 v[72:73], v[8:9]
	v_mov_b64_e32 v[70:71], v[6:7]
	v_mov_b64_e32 v[68:69], v[4:5]
	v_mov_b64_e32 v[66:67], v[2:3]
	v_mov_b64_e32 v[46:47], v[14:15]
	v_mov_b64_e32 v[44:45], v[12:13]
	v_mov_b64_e32 v[42:43], v[10:11]
	v_mov_b64_e32 v[40:41], v[8:9]
	v_mov_b64_e32 v[38:39], v[6:7]
	v_mov_b64_e32 v[36:37], v[4:5]
	v_mov_b64_e32 v[34:35], v[2:3]
	s_waitcnt vmcnt(0)
	s_branch .LBB0_732

.LBB0_732:
	s_waitcnt vmcnt(0)
	s_barrier
	s_and_b32 s6, s71, 0x10000
	s_add_i32 s7, s76, 3
	s_cmp_ge_u32 s7, s74
	s_cbranch_scc1 .LBB0_734
	s_lshr_b32 s7, s7, 2
	s_and_b32 s8, s75, 0xc000
	s_mul_hi_u32 s9, s7, 0x180000
	s_mul_i32 s7, s7, 0x180000
	s_or_b32 s8, s7, s8
	s_lshl_b64 s[8:9], s[8:9], 1
	s_add_u32 s10, s94, s8
	s_addc_u32 s11, s95, s9
	s_add_u32 s12, s88, s8
	s_addc_u32 s13, s89, s9
	s_add_u32 s8, s90, s8
	s_addc_u32 s9, s91, s9
	s_sub_i32 s7, s70, s6
	s_mov_b32 s14, m0
	s_mov_b32 m0, s7
	s_nop 0
	global_load_lds_dwordx4 v243, s[10:11]
	s_add_u32 m0, m0, 0x2000
	s_nop 0
	global_load_lds_dwordx4 v244, s[10:11]
	s_add_u32 m0, m0, 0x2000
	s_nop 0
	global_load_lds_dwordx4 v243, s[12:13]
	s_add_u32 m0, m0, 0x2000
	s_nop 0
	global_load_lds_dwordx4 v244, s[12:13]
	s_add_u32 m0, m0, 0x2000
	s_nop 0
	global_load_lds_dwordx4 v245, s[8:9]
	s_add_u32 m0, m0, 0x2000
	s_nop 0
	global_load_lds_dwordx4 v246, s[8:9]
	s_add_u32 m0, m0, 0x2000
	s_nop 0
	global_load_lds_dwordx4 v247, s[8:9]
	s_add_u32 m0, m0, 0x2000
	s_nop 0
	global_load_lds_dwordx4 v248, s[8:9]
	s_mov_b32 m0, s14

.LBB0_749:
	v_readlane_b32 s0, v255, 15
	s_xor_b32 s7, s0, 15
	s_lshl_b32 s0, s7, 7
	v_readlane_b32 s1, v255, 6
	s_or_b32 s76, s0, s1
	v_readlane_b32 s0, v255, 13
	s_andn2_b32 s4, 15, s0
	s_lshl_b32 s0, s4, 7
	s_lshl_b32 s10, s6, 11
	s_or_b32 s0, s0, 64
	s_lshl_b32 s1, s4, 15
	s_lshl_b32 s88, s4, 1
	s_lshl_b32 s4, s6, 3
	s_mulk_i32 s6, 0xc0
	s_ashr_i32 s8, s3, 31
	s_mul_hi_i32 s5, s4, 24
	s_add_u32 s4, s6, s3
	s_addc_u32 s5, s5, s8
	s_lshl_b64 s[4:5], s[4:5], 17
	v_readlane_b32 s8, v254, 45
	v_readlane_b32 s9, v254, 46
	s_add_u32 s89, s8, s4
	s_addc_u32 s90, s9, s5
	v_readlane_b32 s8, v254, 47
	v_readlane_b32 s9, v254, 48
	s_add_u32 s91, s8, s4
	s_addc_u32 s94, s9, s5
	s_lshl_b32 s4, s7, 15
	s_lshr_b32 s5, s7, 1
	s_bitset1_b32 s4, 14
	s_mul_i32 s5, s5, 0x180000
	s_and_b32 s4, s4, 0xc000
	s_lshl_b32 s95, s7, 1
	s_or_b32 s4, s4, s5
	s_add_i32 s95, s95, 2
	s_lshl_b32 s8, s4, 1
	v_add_u32_e32 v1, s85, v216
	s_add_u32 s4, s89, s8
	v_ashrrev_i32_e32 v2, 4, v1
	s_addc_u32 s5, s90, 0
	v_xor_b32_e32 v5, v2, v216
	s_add_u32 s74, s89, 0x100
	v_lshlrev_b32_e32 v2, 9, v2
	v_lshlrev_b32_e32 v5, 4, v5
	v_ashrrev_i32_e32 v6, 5, v1
	s_addc_u32 s75, s90, 0
	v_and_or_b32 v2, v5, s2, v2
	v_lshlrev_b32_e32 v5, 4, v1
	v_lshrrev_b32_e32 v7, 2, v1
	v_and_b32_e32 v8, 0x7ffff0, v6
	v_lshrrev_b32_e32 v9, 1, v1
	v_lshrrev_b32_e32 v6, 1, v6
	v_lshlrev_b32_e32 v1, 1, v1
	s_add_u32 s6, s74, s8
	v_and_b32_e32 v9, 8, v9
	v_and_b32_e32 v6, 4, v6
	v_and_or_b32 v7, v7, 3, v8
	v_and_b32_e32 v1, 0x1c0, v1
	s_addc_u32 s7, s75, 0
	v_or3_b32 v6, v7, v6, v9
	v_and_or_b32 v1, v5, 48, v1
	s_add_u32 s8, s91, s8
	v_lshl_or_b32 v1, v6, 9, v1
	s_addc_u32 s9, s94, 0
	s_lshl_b32 s3, s3, 8
	v_ashrrev_i32_e32 v218, 5, v216
	v_add_u32_e32 v5, 0x2000, v1
	s_add_i32 s3, s3, s20
	v_add_u32_e32 v6, 0x4000, v1
	v_add_u32_e32 v7, 0x6000, v1
	v_add_u32_e32 v8, 0x4000, v2
	v_readlane_b32 s12, v254, 62
	s_mov_b32 s11, m0
	s_mov_b32 m0, s12
	s_nop 0
	global_load_lds_dwordx4 v2, s[4:5]
	s_add_u32 m0, m0, 0x2000
	s_nop 0
	global_load_lds_dwordx4 v8, s[4:5]
	s_add_u32 m0, m0, 0x2000
	s_nop 0
	global_load_lds_dwordx4 v2, s[6:7]
	s_add_u32 m0, m0, 0x2000
	s_nop 0
	global_load_lds_dwordx4 v8, s[6:7]
	s_add_u32 m0, m0, 0x2000
	s_nop 0
	global_load_lds_dwordx4 v1, s[8:9]
	s_add_u32 m0, m0, 0x2000
	s_nop 0
	global_load_lds_dwordx4 v5, s[8:9]
	s_add_u32 m0, m0, 0x2000
	s_nop 0
	global_load_lds_dwordx4 v6, s[8:9]
	s_add_u32 m0, m0, 0x2000
	s_nop 0
	global_load_lds_dwordx4 v7, s[8:9]
	s_mov_b32 m0, s11
	v_mov_b32_e32 v243, v2
	v_mov_b32_e32 v244, v8
	v_mov_b32_e32 v245, v1
	v_mov_b32_e32 v246, v5
	v_mov_b32_e32 v247, v6
	v_mov_b32_e32 v248, v7
	s_or_b32 s4, s10, s76
	v_lshl_add_u32 v5, v218, 3, s3
	v_and_b32_e32 v217, 31, v216
	v_writelane_b32 v255, s3, 15
	s_ashr_i32 s3, s4, 8
	v_ashrrev_i32_e32 v2, 8, v5
	v_or_b32_e32 v1, s76, v217
	v_writelane_b32 v255, s4, 13
	v_mad_u64_u32 v[6:7], s[4:5], s3, 24, v[2:3]
	v_ashrrev_i32_e32 v7, 31, v6
	v_lshlrev_b32_e32 v1, 8, v1
	v_and_b32_e32 v2, 0xf8, v5
	s_mov_b32 s3, 0xff00
	v_readlane_b32 s4, v254, 41
	v_and_or_b32 v1, v1, s3, v2
	v_lshlrev_b64 v[6:7], 17, v[6:7]
	v_readlane_b32 s5, v254, 42
	v_lshlrev_b32_e32 v2, 1, v1
	v_exp_f32_e32 v1, v4
	v_lshl_add_u64 v[6:7], s[4:5], 0, v[6:7]
	v_lshl_add_u64 v[6:7], v[6:7], 0, v[2:3]
	global_load_dwordx4 v[178:181], v[6:7], off
	global_load_dwordx4 v[182:185], v[6:7], off offset:32
	global_load_dwordx4 v[186:189], v[6:7], off offset:64
	global_load_dwordx4 v[190:193], v[6:7], off offset:96
	global_load_dwordx4 v[194:197], v[6:7], off offset:128
	global_load_dwordx4 v[198:201], v[6:7], off offset:160
	global_load_dwordx4 v[202:205], v[6:7], off offset:192
	global_load_dwordx4 v[206:209], v[6:7], off offset:224
	v_lshlrev_b32_e32 v221, 4, v218
	v_lshlrev_b32_e32 v220, 4, v216
	v_lshlrev_b32_e32 v219, 3, v216
	v_mul_f32_e32 v228, 0x3fb8aa3b, v1
	v_add_u32_e32 v1, 0xc0, v221
	v_lshlrev_b32_e32 v2, 1, v216
	v_and_b32_e32 v5, 0x118, v219
	v_bitop3_b32 v230, v1, v220, s2 bitop3:0x78
	v_add_u32_e32 v1, 0xe0, v221
	v_readlane_b32 s6, v254, 61
	v_and_b32_e32 v4, 0xc0, v220
	v_bitop3_b32 v231, v1, v220, s2 bitop3:0x78
	v_lshl_add_u32 v232, v217, 2, s6
	v_and_or_b32 v1, v2, 32, v5
	v_readlane_b32 s6, v255, 8
	v_add_u32_e32 v6, 32, v221
	v_add_u32_e32 v7, 64, v221
	v_add3_u32 v233, v4, s6, v1
	v_readlane_b32 s6, v255, 7
	v_add_u32_e32 v8, 0x60, v221
	v_add_u32_e32 v9, 0x80, v221
	v_add_u32_e32 v10, 0xa0, v221
	v_lshlrev_b32_e32 v2, 2, v218
	v_add_u32_e32 v1, s6, v217
	v_mov_b32_e32 v16, v3
	v_mov_b32_e32 v17, v3
	v_readlane_b32 s3, v255, 1
	v_bitop3_b32 v224, v6, v220, s2 bitop3:0x78
	v_bitop3_b32 v225, v7, v220, s2 bitop3:0x78
	v_bitop3_b32 v226, v8, v220, s2 bitop3:0x78
	v_bitop3_b32 v227, v9, v220, s2 bitop3:0x78
	v_bitop3_b32 v229, v10, v220, s2 bitop3:0x78
	v_sub_u32_e32 v234, v1, v2
	v_mov_b32_e32 v2, v3
	v_mov_b32_e32 v4, v3
	v_mov_b32_e32 v5, v3
	v_mov_b32_e32 v6, v3
	v_mov_b32_e32 v7, v3
	v_mov_b32_e32 v8, v3
	v_mov_b32_e32 v9, v3
	v_mov_b32_e32 v10, v3
	v_mov_b32_e32 v11, v3
	v_mov_b32_e32 v12, v3
	v_mov_b32_e32 v13, v3
	v_mov_b32_e32 v14, v3
	v_mov_b32_e32 v15, v3
	v_mov_b64_e32 v[128:129], v[16:17]
	v_mov_b64_e32 v[96:97], v[16:17]
	v_mov_b64_e32 v[64:65], v[16:17]
	v_mov_b64_e32 v[32:33], v[16:17]
	v_mov_b64_e32 v[144:145], v[16:17]
	v_mov_b64_e32 v[112:113], v[16:17]
	v_mov_b64_e32 v[80:81], v[16:17]
	v_mov_b64_e32 v[48:49], v[16:17]
	s_mov_b32 s71, 1
	v_lshl_add_u32 v222, v217, 8, s3
	v_bitop3_b32 v223, v220, v221, s2 bitop3:0x6c
	s_or_b32 s3, s76, 31
	v_cmp_gt_u32_e64 s[4:5], 32, v216
	s_mov_b32 s72, 0
	v_mov_b32_e32 v235, 0xf149f2ca
	v_mov_b32_e32 v236, 0
	v_mov_b64_e32 v[126:127], v[14:15]
	v_mov_b64_e32 v[124:125], v[12:13]
	v_mov_b64_e32 v[122:123], v[10:11]
	v_mov_b64_e32 v[120:121], v[8:9]
	v_mov_b64_e32 v[118:119], v[6:7]
	v_mov_b64_e32 v[116:117], v[4:5]
	v_mov_b64_e32 v[114:115], v[2:3]
	v_mov_b64_e32 v[94:95], v[14:15]
	v_mov_b64_e32 v[92:93], v[12:13]
	v_mov_b64_e32 v[90:91], v[10:11]
	v_mov_b64_e32 v[88:89], v[8:9]
	v_mov_b64_e32 v[86:87], v[6:7]
	v_mov_b64_e32 v[84:85], v[4:5]
	v_mov_b64_e32 v[82:83], v[2:3]
	v_mov_b64_e32 v[62:63], v[14:15]
	v_mov_b64_e32 v[60:61], v[12:13]
	v_mov_b64_e32 v[58:59], v[10:11]
	v_mov_b64_e32 v[56:57], v[8:9]
	v_mov_b64_e32 v[54:55], v[6:7]
	v_mov_b64_e32 v[52:53], v[4:5]
	v_mov_b64_e32 v[50:51], v[2:3]
	v_mov_b64_e32 v[30:31], v[14:15]
	v_mov_b64_e32 v[28:29], v[12:13]
	v_mov_b64_e32 v[26:27], v[10:11]
	v_mov_b64_e32 v[24:25], v[8:9]
	v_mov_b64_e32 v[22:23], v[6:7]
	v_mov_b64_e32 v[20:21], v[4:5]
	v_mov_b64_e32 v[18:19], v[2:3]
	v_mov_b64_e32 v[142:143], v[14:15]
	v_mov_b64_e32 v[140:141], v[12:13]
	v_mov_b64_e32 v[138:139], v[10:11]
	v_mov_b64_e32 v[136:137], v[8:9]
	v_mov_b64_e32 v[134:135], v[6:7]
	v_mov_b64_e32 v[132:133], v[4:5]
	v_mov_b64_e32 v[130:131], v[2:3]
	v_mov_b64_e32 v[110:111], v[14:15]
	v_mov_b64_e32 v[108:109], v[12:13]
	v_mov_b64_e32 v[106:107], v[10:11]
	v_mov_b64_e32 v[104:105], v[8:9]
	v_mov_b64_e32 v[102:103], v[6:7]
	v_mov_b64_e32 v[100:101], v[4:5]
	v_mov_b64_e32 v[98:99], v[2:3]
	v_mov_b64_e32 v[78:79], v[14:15]
	v_mov_b64_e32 v[76:77], v[12:13]
	v_mov_b64_e32 v[74:75], v[10:11]
	v_mov_b64_e32 v[72:73], v[8:9]
	v_mov_b64_e32 v[70:71], v[6:7]
	v_mov_b64_e32 v[68:69], v[4:5]
	v_mov_b64_e32 v[66:67], v[2:3]
	v_mov_b64_e32 v[46:47], v[14:15]
	v_mov_b64_e32 v[44:45], v[12:13]
	v_mov_b64_e32 v[42:43], v[10:11]
	v_mov_b64_e32 v[40:41], v[8:9]
	v_mov_b64_e32 v[38:39], v[6:7]
	v_mov_b64_e32 v[36:37], v[4:5]
	v_mov_b64_e32 v[34:35], v[2:3]
	s_waitcnt vmcnt(0)
	s_branch .LBB0_753

.LBB0_753:
	s_waitcnt vmcnt(0)
	s_barrier
	s_and_b32 s6, s72, 0x10000
	s_cmp_ge_u32 s71, s95
	s_cbranch_scc1 .LBB0_755
	s_ashr_i32 s7, s88, 2
	s_and_b32 s8, s1, 0xc000
	s_mul_hi_i32 s9, s7, 0x180000
	s_mul_i32 s7, s7, 0x180000
	s_or_b32 s8, s7, s8
	s_lshl_b64 s[8:9], s[8:9], 1
	s_add_u32 s10, s89, s8
	s_addc_u32 s11, s90, s9
	s_add_u32 s12, s74, s8
	s_addc_u32 s13, s75, s9
	s_add_u32 s8, s91, s8
	s_addc_u32 s9, s94, s9
	s_sub_i32 s7, s70, s6
	s_mov_b32 s14, m0
	s_mov_b32 m0, s7
	s_nop 0
	global_load_lds_dwordx4 v243, s[10:11]
	s_add_u32 m0, m0, 0x2000
	s_nop 0
	global_load_lds_dwordx4 v244, s[10:11]
	s_add_u32 m0, m0, 0x2000
	s_nop 0
	global_load_lds_dwordx4 v243, s[12:13]
	s_add_u32 m0, m0, 0x2000
	s_nop 0
	global_load_lds_dwordx4 v244, s[12:13]
	s_add_u32 m0, m0, 0x2000
	s_nop 0
	global_load_lds_dwordx4 v245, s[8:9]
	s_add_u32 m0, m0, 0x2000
	s_nop 0
	global_load_lds_dwordx4 v246, s[8:9]
	s_add_u32 m0, m0, 0x2000
	s_nop 0
	global_load_lds_dwordx4 v247, s[8:9]
	s_add_u32 m0, m0, 0x2000
	s_nop 0
	global_load_lds_dwordx4 v248, s[8:9]
	s_mov_b32 m0, s14
